# P6: each workgroup walks its five tiles in reverse row-panel order so the rows the up-projection wrote last are read first (cache reuse across the phase seam)
# baseline (speedup 1.0000x reference)
;     __host__ __device__ bool next(int i, Unit& u) const {
;         const long L = (long)i * G + c; if (L >= nwg) return false;
;         int wgid = (int)L; { const int q = nwg / NXCD, r = nwg % NXCD, xcd = wgid % NXCD, off = wgid / NXCD; wgid = (xcd < r ? xcd * (q + 1) : r * (q + 1) + (xcd - r) * q) + off; }
;         const int nig = WGM * nN, gid = wgid / nig, fm = gid * WGM, gsz = (nM - fm) < WGM ? (nM - fm) : WGM;
;         u.pm = fm + ((wgid % nig) % gsz); u.pn = (wgid % nig) / gsz; return true;
;     }
.Lmy_gb7_done:
.LBB0_415:
	s_or_b64 exec, exec, s[0:1]
	s_barrier
	s_and_b64 vcc, exec, s[2:3]
	v_readfirstlane_b32 s0, v254
	s_cbranch_vccnz .LBB0_418
	s_add_i32 s5, s33, 0x400
	s_lshr_b32 s1, s76, 29
	s_add_i32 s1, s5, s1
	s_ashr_i32 s4, s1, 3
	s_and_b32 s1, s1, -8
	s_sub_i32 s1, s5, s1
	s_cmp_lt_i32 s1, 0
	s_movk_i32 s5, 0xa1
	s_cselect_b32 s5, s5, 0xa0
	s_mul_i32 s1, s1, s5
	s_add_i32 s1, s1, s4
	s_ashr_i32 s4, s1, 31
	s_lshr_b32 s4, s4, 27
	s_add_i32 s4, s1, s4
	s_ashr_i32 s5, s4, 5
	s_and_b32 s4, s4, 0xffe0
	s_sub_i32 s1, s1, s4
	s_bfe_i32 s4, s1, 0x80000
	s_bfe_u32 s4, s4, 0x3000c
	s_add_i32 s4, s1, s4
	s_bfe_i32 s6, s4, 0x80000
	s_and_b32 s4, s4, 0xf8
	s_sub_i32 s1, s1, s4
	s_lshl_b32 s5, s5, 3
	s_sext_i32_i16 s6, s6
	s_sext_i32_i8 s1, s1
	s_add_i32 s38, s5, s1
	s_ashr_i32 s6, s6, 3
	s_and_b64 vcc, exec, s[2:3]
	s_cbranch_vccz .LBB0_419

;     __host__ __device__ bool next(int i, Unit& u) const {
;         const long L = (long)i * G + c; if (L >= nwg) return false;
;         int wgid = (int)L; { const int q = nwg / NXCD, r = nwg % NXCD, xcd = wgid % NXCD, off = wgid / NXCD; wgid = (xcd < r ? xcd * (q + 1) : r * (q + 1) + (xcd - r) * q) + off; }
;         const int nig = WGM * nN, gid = wgid / nig, fm = gid * WGM, gsz = (nM - fm) < WGM ? (nM - fm) : WGM;
;         u.pm = fm + ((wgid % nig) % gsz); u.pn = (wgid % nig) / gsz; return true;
;     }
; template <class Epi, class Sched, bool ALIGN_EPI = false, bool SP2 = false, bool FP8 = false>
; __device__ __forceinline__ void gemm_phase(PG8_LAS unsigned char* lds, const Gemm g, const Sched& S, const Epi& E) {
;     ...
;         const bool has_next = S.next(ui + 1, nxt);
;         const char* nA = has_next ? (const char*)g.A + (size_t)nxt.pm * tstep : cA; const char* nB = has_next ? (const char*)g.Bt + (size_t)nxt.pn * tstep : cB;
.LBB0_424:
	s_add_i32 s59, s59, 1
	s_sub_i32 s34, 4, s59
	s_cmp_lt_i32 s34, 0
	s_cselect_b32 s34, s59, s34
	s_mul_i32 s4, s34, s25
	s_mul_hi_u32 s5, s34, s24
	s_add_i32 s5, s5, s4
	s_mul_i32 s4, s34, s24
	s_add_u32 s34, s4, s33
	s_addc_u32 s35, s5, s76
	v_cmp_gt_i64_e32 vcc, s[34:35], v[168:169]
	v_cmp_lt_i64_e64 s[4:5], s[34:35], v[166:167]
	s_cbranch_vccnz .LBB0_426
	s_ashr_i32 s22, s34, 31
	s_lshr_b32 s22, s22, 29
	s_add_i32 s22, s34, s22
	s_ashr_i32 s23, s22, 3
	s_and_b32 s22, s22, -8
	s_sub_i32 s22, s34, s22
	s_cmp_lt_i32 s22, 0
	s_cselect_b32 s30, s56, 0xa0
	s_mul_i32 s22, s22, s30
	s_add_i32 s22, s22, s23
	s_ashr_i32 s23, s22, 31
	s_lshr_b32 s23, s23, 27
	s_add_i32 s23, s22, s23
	s_ashr_i32 s30, s23, 5
	s_lshl_b32 s30, s30, 3
	s_sub_i32 s31, 0x140, s30
	s_min_i32 s31, s31, 8
	s_abs_i32 s34, s31
	v_cvt_f32_u32_e32 v0, s34
	s_sub_i32 s36, 0, s34
	s_andn2_b32 s23, s23, 31
	s_sub_i32 s23, s22, s23
	v_rcp_iflag_f32_e32 v0, v0
	s_abs_i32 s22, s23
	s_xor_b32 s35, s23, s31
	s_ashr_i32 s35, s35, 31
	v_mul_f32_e32 v0, 0x4f7ffffe, v0
	v_cvt_u32_f32_e32 v0, v0
	s_nop 0
	v_readfirstlane_b32 s37, v0
	s_mul_i32 s36, s36, s37
	s_mul_hi_u32 s36, s37, s36
	s_add_i32 s37, s37, s36
	s_mul_hi_u32 s36, s22, s37
	s_mul_i32 s37, s36, s34
	s_sub_i32 s22, s22, s37
	s_add_i32 s39, s36, 1
	s_sub_i32 s37, s22, s34
	s_cmp_ge_u32 s22, s34
	s_cselect_b32 s36, s39, s36
	s_cselect_b32 s22, s37, s22
	s_add_i32 s37, s36, 1
	s_cmp_ge_u32 s22, s34
	s_cselect_b32 s22, s37, s36
	s_xor_b32 s22, s22, s35
	s_sub_i32 s22, s22, s35
	s_mul_i32 s31, s22, s31
	s_sub_i32 s23, s23, s31
	s_add_i32 s30, s30, s23
